# rmsnorm (NORMMIX/NORM2): all four row loads issued together instead of two dependent halves
# speedup vs baseline: 1.0508x; 1.0005x over previous
; __device__ __forceinline__ uint32_t pk2(float lo, float hi) { typedef float f2 __attribute__((ext_vector_type(2))); const f2 v = {lo, hi}; return __builtin_bit_cast(uint32_t, __builtin_convertvector(v, bf16x2_t)); }
; __device__ __forceinline__ void phase_rmsnorm(const float* x, const float* gain, bf16_t* outb, float* outf) {
;     ...
;     for (int row = blockIdx.x * 4 + wave; row < TOK; row += gridDim.x * 4) {
;         const float* xr = x + (size_t)row * DM + lane * 4;
;         f32x4 v[4]; float s = 0.f;
; #pragma unroll
;         for (int j = 0; j < 4; ++j) { v[j] = *(const f32x4*)(xr + 256 * j); s += v[j].x * v[j].x + v[j].y * v[j].y + v[j].z * v[j].z + v[j].w * v[j].w; }
;         s = wave_sum(s);
;         const float r = rsqrtf(s * (1.f / DM) + EPS);
; #pragma unroll
;         for (int j = 0; j < 4; ++j) {
;             f32x4 o = v[j] * r * g[j];
;             if (outb) { u32x2 w = {pk2(o.x, o.y), pk2(o.z, o.w)}; *(u32x2*)(outb + (size_t)row * DM + lane * 4 + 256 * j) = w; }
;             else *(f32x4*)(outf + (size_t)row * DM + lane * 4 + 256 * j) = o;
;         }
.LBB0_75:
	v_ashrrev_i32_e32 v19, 31, v18
	s_waitcnt vmcnt(38)
	v_lshlrev_b64 v[30:31], 12, v[18:19]
	s_waitcnt vmcnt(34)
	v_lshl_add_u64 v[42:43], v[20:21], 0, v[30:31]
	global_load_dwordx4 v[30:33], v[42:43], off
	global_load_dwordx4 v[34:37], v[42:43], off offset:1024
	global_load_dwordx4 v[38:41], v[42:43], off offset:2048
	s_nop 0
	global_load_dwordx4 v[42:45], v[42:43], off offset:3072
	s_waitcnt vmcnt(3)
	v_mov_b32_e32 v50, v31
	s_waitcnt vmcnt(2)
	v_mov_b32_e32 v51, v35
	v_mov_b32_e32 v48, v30
	v_mov_b32_e32 v49, v34
	v_pk_mul_f32 v[50:51], v[50:51], v[50:51]
	s_nop 0
	v_pk_fma_f32 v[48:49], v[48:49], v[48:49], v[50:51]
	v_mov_b32_e32 v50, v32
	v_mov_b32_e32 v51, v36
	v_pk_fma_f32 v[48:49], v[50:51], v[50:51], v[48:49]
	v_mov_b32_e32 v50, v33
	v_mov_b32_e32 v51, v37
	v_pk_fma_f32 v[46:47], v[50:51], v[50:51], v[48:49]
	v_add_f32_e32 v0, v46, v47
	s_waitcnt vmcnt(1)
	v_mov_b32_e32 v50, v39
	s_waitcnt vmcnt(0)
	v_mov_b32_e32 v51, v43
	v_mov_b32_e32 v48, v38
	v_mov_b32_e32 v49, v42
	v_pk_mul_f32 v[50:51], v[50:51], v[50:51]
	s_nop 0
	v_pk_fma_f32 v[48:49], v[48:49], v[48:49], v[50:51]
	v_mov_b32_e32 v50, v40
	v_mov_b32_e32 v51, v44
	v_pk_fma_f32 v[48:49], v[50:51], v[50:51], v[48:49]
	v_mov_b32_e32 v50, v41
	v_mov_b32_e32 v51, v45
	v_pk_fma_f32 v[48:49], v[50:51], v[50:51], v[48:49]
	s_nop 0
	v_add_f32_e32 v0, v0, v48
	v_add_f32_e32 v0, v0, v49
	ds_bpermute_b32 v46, v24, v0
	s_waitcnt lgkmcnt(0)
	v_add_f32_e32 v0, v0, v46
	ds_bpermute_b32 v46, v25, v0
	s_waitcnt lgkmcnt(0)
	v_add_f32_e32 v0, v0, v46
	ds_bpermute_b32 v46, v26, v0
	s_waitcnt lgkmcnt(0)
	v_add_f32_e32 v0, v0, v46
	ds_bpermute_b32 v46, v27, v0
	s_waitcnt lgkmcnt(0)
	v_add_f32_e32 v0, v0, v46
	ds_bpermute_b32 v46, v28, v0
	s_waitcnt lgkmcnt(0)
	v_add_f32_e32 v0, v0, v46
	ds_bpermute_b32 v46, v29, v0
	s_waitcnt lgkmcnt(0)
	v_add_f32_e32 v0, v0, v46
	v_fmamk_f32 v0, v0, 0x3a800000, v178
	v_cmp_gt_f32_e32 vcc, s8, v0
	v_mul_f32_e32 v46, 0x4b800000, v0
	s_nop 0
	v_cndmask_b32_e32 v0, v0, v46, vcc
	v_rsq_f32_e32 v0, v0
	s_nop 0
	v_mul_f32_e32 v46, 0x45800000, v0
	v_cndmask_b32_e32 v0, v0, v46, vcc
	v_pk_mul_f32 v[30:31], v[30:31], v[0:1] op_sel_hi:[1,0]
	v_pk_mul_f32 v[32:33], v[32:33], v[0:1] op_sel_hi:[1,0]
	v_lshlrev_b64 v[46:47], 11, v[18:19]
	v_pk_mul_f32 v[32:33], v[4:5], v[32:33]
	v_pk_mul_f32 v[30:31], v[2:3], v[30:31]
	v_lshl_add_u64 v[46:47], v[22:23], 0, v[46:47]
	v_cvt_pk_bf16_f32 v30, v30, v31
	v_cvt_pk_bf16_f32 v31, v32, v33
	global_store_dwordx2 v[46:47], v[30:31], off
	v_pk_mul_f32 v[30:31], v[34:35], v[0:1] op_sel_hi:[1,0]
	v_pk_mul_f32 v[32:33], v[36:37], v[0:1] op_sel_hi:[1,0]
	v_pk_mul_f32 v[30:31], v[6:7], v[30:31]
	v_pk_mul_f32 v[32:33], v[8:9], v[32:33]
	v_cvt_pk_bf16_f32 v30, v30, v31
	v_cvt_pk_bf16_f32 v31, v32, v33
	global_store_dwordx2 v[46:47], v[30:31], off offset:512
	v_pk_mul_f32 v[30:31], v[38:39], v[0:1] op_sel_hi:[1,0]
	v_pk_mul_f32 v[32:33], v[40:41], v[0:1] op_sel_hi:[1,0]
	v_pk_mul_f32 v[30:31], v[10:11], v[30:31]
	v_pk_mul_f32 v[32:33], v[12:13], v[32:33]
	v_cvt_pk_bf16_f32 v30, v30, v31
	v_cvt_pk_bf16_f32 v31, v32, v33
	global_store_dwordx2 v[46:47], v[30:31], off offset:1024
	v_pk_mul_f32 v[30:31], v[42:43], v[0:1] op_sel_hi:[1,0]
	v_pk_mul_f32 v[32:33], v[44:45], v[0:1] op_sel_hi:[1,0]
	v_add_u32_e32 v18, s3, v18
	v_pk_mul_f32 v[32:33], v[16:17], v[32:33]
	v_pk_mul_f32 v[30:31], v[14:15], v[30:31]
	v_cmp_lt_i32_e32 vcc, s9, v18
	v_cvt_pk_bf16_f32 v30, v30, v31
	v_cvt_pk_bf16_f32 v31, v32, v33
	s_or_b64 s[4:5], vcc, s[4:5]
	global_store_dwordx2 v[46:47], v[30:31], off offset:1536
	s_andn2_b64 exec, exec, s[4:5]
	s_cbranch_execnz .LBB0_75

; __device__ __forceinline__ uint32_t pk2(float lo, float hi) { typedef float f2 __attribute__((ext_vector_type(2))); const f2 v = {lo, hi}; return __builtin_bit_cast(uint32_t, __builtin_convertvector(v, bf16x2_t)); }
; __device__ __forceinline__ void phase_rmsnorm(const float* x, const float* gain, bf16_t* outb, float* outf) {
;     ...
;     for (int row = blockIdx.x * 4 + wave; row < TOK; row += gridDim.x * 4) {
;         const float* xr = x + (size_t)row * DM + lane * 4;
;         f32x4 v[4]; float s = 0.f;
; #pragma unroll
;         for (int j = 0; j < 4; ++j) { v[j] = *(const f32x4*)(xr + 256 * j); s += v[j].x * v[j].x + v[j].y * v[j].y + v[j].z * v[j].z + v[j].w * v[j].w; }
;         s = wave_sum(s);
;         const float r = rsqrtf(s * (1.f / DM) + EPS);
; #pragma unroll
;         for (int j = 0; j < 4; ++j) {
;             f32x4 o = v[j] * r * g[j];
;             if (outb) { u32x2 w = {pk2(o.x, o.y), pk2(o.z, o.w)}; *(u32x2*)(outb + (size_t)row * DM + lane * 4 + 256 * j) = w; }
;             else *(f32x4*)(outf + (size_t)row * DM + lane * 4 + 256 * j) = o;
;         }
.LBB0_766:
	v_ashrrev_i32_e32 v19, 31, v18
	s_waitcnt vmcnt(38)
	v_lshlrev_b64 v[30:31], 12, v[18:19]
	s_waitcnt vmcnt(34)
	v_lshl_add_u64 v[42:43], v[20:21], 0, v[30:31]
	global_load_dwordx4 v[30:33], v[42:43], off
	global_load_dwordx4 v[34:37], v[42:43], off offset:1024
	global_load_dwordx4 v[38:41], v[42:43], off offset:2048
	s_nop 0
	global_load_dwordx4 v[42:45], v[42:43], off offset:3072
	s_waitcnt vmcnt(3)
	v_mov_b32_e32 v50, v31
	s_waitcnt vmcnt(2)
	v_mov_b32_e32 v51, v35
	v_mov_b32_e32 v48, v30
	v_mov_b32_e32 v49, v34
	v_pk_mul_f32 v[50:51], v[50:51], v[50:51]
	s_nop 0
	v_pk_fma_f32 v[48:49], v[48:49], v[48:49], v[50:51]
	v_mov_b32_e32 v50, v32
	v_mov_b32_e32 v51, v36
	v_pk_fma_f32 v[48:49], v[50:51], v[50:51], v[48:49]
	v_mov_b32_e32 v50, v33
	v_mov_b32_e32 v51, v37
	v_pk_fma_f32 v[46:47], v[50:51], v[50:51], v[48:49]
	v_add_f32_e32 v0, v46, v47
	s_waitcnt vmcnt(1)
	v_mov_b32_e32 v50, v39
	s_waitcnt vmcnt(0)
	v_mov_b32_e32 v51, v43
	v_mov_b32_e32 v48, v38
	v_mov_b32_e32 v49, v42
	v_pk_mul_f32 v[50:51], v[50:51], v[50:51]
	s_nop 0
	v_pk_fma_f32 v[48:49], v[48:49], v[48:49], v[50:51]
	v_mov_b32_e32 v50, v40
	v_mov_b32_e32 v51, v44
	v_pk_fma_f32 v[48:49], v[50:51], v[50:51], v[48:49]
	v_mov_b32_e32 v50, v41
	v_mov_b32_e32 v51, v45
	v_pk_fma_f32 v[48:49], v[50:51], v[50:51], v[48:49]
	s_nop 0
	v_add_f32_e32 v0, v0, v48
	v_add_f32_e32 v0, v0, v49
	ds_bpermute_b32 v46, v24, v0
	s_waitcnt lgkmcnt(0)
	v_add_f32_e32 v0, v0, v46
	ds_bpermute_b32 v46, v25, v0
	s_waitcnt lgkmcnt(0)
	v_add_f32_e32 v0, v0, v46
	ds_bpermute_b32 v46, v26, v0
	s_waitcnt lgkmcnt(0)
	v_add_f32_e32 v0, v0, v46
	ds_bpermute_b32 v46, v27, v0
	s_waitcnt lgkmcnt(0)
	v_add_f32_e32 v0, v0, v46
	ds_bpermute_b32 v46, v28, v0
	s_waitcnt lgkmcnt(0)
	v_add_f32_e32 v0, v0, v46
	ds_bpermute_b32 v46, v29, v0
	s_waitcnt lgkmcnt(0)
	v_add_f32_e32 v0, v0, v46
	v_fmamk_f32 v0, v0, 0x3a800000, v178
	v_cmp_gt_f32_e32 vcc, s6, v0
	v_mul_f32_e32 v46, 0x4b800000, v0
	s_nop 0
	v_cndmask_b32_e32 v0, v0, v46, vcc
	v_rsq_f32_e32 v0, v0
	s_nop 0
	v_mul_f32_e32 v46, 0x45800000, v0
	v_cndmask_b32_e32 v0, v0, v46, vcc
	v_pk_mul_f32 v[30:31], v[30:31], v[0:1] op_sel_hi:[1,0]
	v_pk_mul_f32 v[32:33], v[32:33], v[0:1] op_sel_hi:[1,0]
	v_lshlrev_b64 v[46:47], 11, v[18:19]
	v_pk_mul_f32 v[32:33], v[4:5], v[32:33]
	v_pk_mul_f32 v[30:31], v[2:3], v[30:31]
	v_lshl_add_u64 v[46:47], v[22:23], 0, v[46:47]
	v_cvt_pk_bf16_f32 v30, v30, v31
	v_cvt_pk_bf16_f32 v31, v32, v33
	global_store_dwordx2 v[46:47], v[30:31], off
	v_pk_mul_f32 v[30:31], v[34:35], v[0:1] op_sel_hi:[1,0]
	v_pk_mul_f32 v[32:33], v[36:37], v[0:1] op_sel_hi:[1,0]
	v_pk_mul_f32 v[30:31], v[6:7], v[30:31]
	v_pk_mul_f32 v[32:33], v[8:9], v[32:33]
	v_cvt_pk_bf16_f32 v30, v30, v31
	v_cvt_pk_bf16_f32 v31, v32, v33
	global_store_dwordx2 v[46:47], v[30:31], off offset:512
	v_pk_mul_f32 v[30:31], v[38:39], v[0:1] op_sel_hi:[1,0]
	v_pk_mul_f32 v[32:33], v[40:41], v[0:1] op_sel_hi:[1,0]
	v_pk_mul_f32 v[30:31], v[10:11], v[30:31]
	v_pk_mul_f32 v[32:33], v[12:13], v[32:33]
	v_cvt_pk_bf16_f32 v30, v30, v31
	v_cvt_pk_bf16_f32 v31, v32, v33
	global_store_dwordx2 v[46:47], v[30:31], off offset:1024
	v_pk_mul_f32 v[30:31], v[42:43], v[0:1] op_sel_hi:[1,0]
	v_pk_mul_f32 v[32:33], v[44:45], v[0:1] op_sel_hi:[1,0]
	v_add_u32_e32 v18, s4, v18
	v_pk_mul_f32 v[32:33], v[16:17], v[32:33]
	v_pk_mul_f32 v[30:31], v[14:15], v[30:31]
	v_cmp_lt_i32_e32 vcc, s7, v18
	v_cvt_pk_bf16_f32 v30, v30, v31
	v_cvt_pk_bf16_f32 v31, v32, v33
	s_or_b64 s[2:3], vcc, s[2:3]
	global_store_dwordx2 v[46:47], v[30:31], off offset:1536
	s_andn2_b64 exec, exec, s[2:3]
	s_cbranch_execnz .LBB0_766
